# dependency poll loops back off longer between record reads (s_sleep 8) to keep polling traffic away from the busy workgroups
# baseline (speedup 1.0000x reference)
.Lm1poll_a:
	global_load_dwordx4 v[228:231], v226, s[64:65] sc1
	s_waitcnt vmcnt(0)
	v_cmp_ne_u32_e32 vcc, s52, v228
	s_cbranch_vccz .Lm1ok_a
	s_sleep 8
	s_add_i32 s53, s53, -1
	s_cmp_lg_u32 s53, 0
	s_cbranch_scc1 .Lm1poll_a

.Lip_poll:
	global_load_dwordx4 v[68:71], v66, s[46:47] sc1
	s_waitcnt vmcnt(0)
	v_cmp_ne_u32_e32 vcc, s64, v68
	s_cbranch_vccz .Lip_ok
	s_sleep 8
	s_add_i32 s65, s65, -1
	s_cmp_lg_u32 s65, 0
	s_cbranch_scc1 .Lip_poll

.Lln2dep_poll:
	global_load_dwordx4 v[228:231], v226, s[50:51] sc1
	s_waitcnt vmcnt(0)
	v_cmp_ne_u32_e32 vcc, s52, v228
	s_cbranch_vccz .Lln2dep_ok
	s_sleep 8
	s_add_i32 s53, s53, -1
	s_cmp_lg_u32 s53, 0
	s_cbranch_scc1 .Lln2dep_poll
